# attention loop: waves 0-3 at static priority 3 for the whole key loop (the two waves of a SIMD serialise instead of interleaving)
# baseline (speedup 1.0000x reference)
.Lfa_entry:
	s_cmp_lt_u32 s24, 0x1000
	s_cbranch_scc0 .Lfa_noprio
	s_setprio 3

.Lfa_bexit:
	s_setprio 0
	s_branch .LBB0_221
